# norm phase: streaming (nt) hint on the single-use f32 x row loads so the bf16 norm output stays in L2 for the following GEMM
# baseline (speedup 1.0000x reference)
.LBB0_431:
	s_mov_b64 s[12:13], s[68:69]
	s_mov_b64 s[14:15], s[68:69]
	s_mov_b64 s[10:11], s[68:69]
	s_mov_b64 s[8:9], s[68:69]
	v_mov_b32_e32 v0, v196
	v_mov_b32_e32 v1, v196
	v_readlane_b32 s0, v251, 20
	v_ashrrev_i32_e32 v10, 6, v1
	s_mul_i32 s96, s22, 0xc00
	v_add_u32_e32 v14, s0, v10
	v_cmp_gt_i32_e32 vcc, s73, v14
	v_readlane_b32 s1, v251, 21
	s_and_saveexec_b64 s[4:5], vcc
	s_cbranch_execz .LBB0_434
	s_load_dwordx2 s[0:1], s[14:15], 0xb8
	s_nop 0
	s_load_dwordx2 s[12:13], s[12:13], 0x28
	v_readlane_b32 s14, v251, 53
	v_readlane_b32 s15, v251, 54
	s_lshl_b64 s[14:15], s[14:15], 2
	s_load_dwordx2 s[10:11], s[10:11], 0xb8
	s_waitcnt lgkmcnt(0)
	s_add_u32 s16, s0, s14
	s_addc_u32 s17, s1, s15
	s_lshl_b64 s[0:1], s[96:97], 2
	s_add_u32 s16, s16, s0
	s_addc_u32 s17, s17, s1
	s_add_u32 s10, s10, s14
	s_addc_u32 s11, s11, s15
	s_add_u32 s0, s10, s0
	v_readlane_b32 s10, v250, 10
	s_mul_i32 s10, s10, 3
	s_addc_u32 s1, s11, s1
	s_add_i32 s10, s22, s10
	s_lshl_b32 s10, s10, 10
	s_mov_b32 s11, s97
	s_lshl_b64 s[10:11], s[10:11], 2
	v_and_b32_e32 v21, 63, v0
	s_add_u32 s10, s12, s10
	s_addc_u32 s11, s13, s11
	v_lshlrev_b32_e32 v92, 4, v21
	global_load_dwordx4 v[0:3], v92, s[10:11]
	v_lshl_add_u64 v[6:7], s[0:1], 0, v[92:93]
	s_mov_b64 s[0:1], 0x1000
	v_cmp_lt_i32_e32 vcc, v204, v198
	v_lshl_add_u64 v[6:7], v[6:7], 0, s[0:1]
	v_readlane_b32 s0, v251, 20
	s_load_dwordx2 s[8:9], s[8:9], 0xb8
	v_cndmask_b32_e32 v4, v197, v204, vcc
	v_cmp_lt_i32_e32 vcc, v205, v198
	v_ashrrev_i32_e32 v11, 31, v10
	v_readlane_b32 s1, v251, 21
	v_lshlrev_b32_e32 v15, 2, v4
	v_cndmask_b32_e32 v4, v197, v205, vcc
	v_cmp_lt_i32_e32 vcc, v203, v198
	v_lshl_add_u64 v[12:13], s[0:1], 0, v[10:11]
	v_lshlrev_b32_e32 v16, 2, v4
	v_cndmask_b32_e32 v4, v197, v203, vcc
	v_cmp_lt_i32_e32 vcc, v202, v198
	v_lshlrev_b64 v[10:11], 12, v[12:13]
	v_lshlrev_b32_e32 v17, 2, v4
	v_cndmask_b32_e32 v4, v197, v202, vcc
	v_cmp_lt_i32_e32 vcc, v201, v198
	v_or_b32_e32 v10, v10, v92
	v_lshlrev_b64 v[12:13], 11, v[12:13]
	v_lshlrev_b32_e32 v18, 2, v4
	v_cndmask_b32_e32 v4, v197, v201, vcc
	v_cmp_lt_i32_e32 vcc, v199, v198
	v_lshl_add_u64 v[10:11], s[6:7], 0, v[10:11]
	s_mov_b64 s[0:1], 0x800
	v_lshl_or_b32 v12, v21, 3, v12
	v_lshlrev_b32_e32 v19, 2, v4
	v_cndmask_b32_e32 v4, v197, v199, vcc
	v_lshl_add_u64 v[10:11], v[10:11], 0, s[0:1]
	s_waitcnt lgkmcnt(0)
	v_lshl_add_u64 v[12:13], s[8:9], 0, v[12:13]
	s_mov_b64 s[0:1], 0xe46c400
	v_lshlrev_b32_e32 v20, 2, v4
	v_lshl_add_u64 v[4:5], s[10:11], 0, v[92:93]
	v_lshl_add_u64 v[8:9], s[16:17], 0, v[92:93]
	v_lshl_add_u64 v[12:13], v[12:13], 0, s[0:1]
	s_mov_b64 s[6:7], 0
	s_cmp_lg_u32 s30, 0x100
	s_cbranch_scc1 .LBB0_433
	v_ashrrev_i32_e32 v21, 11, v14
	v_mul_hi_i32_i24_e32 v23, 0x2400, v21
	v_mul_i32_i24_e32 v22, 0x2400, v21
	v_lshlrev_b64 v[22:23], 2, v[22:23]
	v_lshl_add_u64 v[6:7], v[6:7], 0, v[22:23]
	v_lshl_add_u64 v[8:9], v[8:9], 0, v[22:23]
	global_load_dwordx4 v[24:27], v[6:7], off
	global_load_dwordx4 v[28:31], v[6:7], off offset:1024
	global_load_dwordx4 v[32:35], v[6:7], off offset:2048
	global_load_dwordx4 v[36:39], v[6:7], off offset:3072
	global_load_dwordx4 v[52:55], v[8:9], off
	global_load_dwordx4 v[56:59], v[8:9], off offset:1024
	global_load_dwordx4 v[60:63], v[8:9], off offset:2048
	global_load_dwordx4 v[64:67], v[8:9], off offset:3072
	global_load_dwordx4 v[40:43], v[4:5], off offset:1024
	global_load_dwordx4 v[44:47], v[4:5], off offset:2048
	global_load_dwordx4 v[48:51], v[4:5], off offset:3072
	v_lshl_add_u64 v[22:23], v[10:11], 0, s[34:35]
	global_load_dwordx4 v[96:99], v[10:11], off offset:-2048 nt
	global_load_dwordx4 v[100:103], v[10:11], off offset:-1024 nt
	global_load_dwordx4 v[104:107], v[10:11], off nt
	global_load_dwordx4 v[108:111], v[10:11], off offset:1024 nt
	v_lshl_add_u64 v[68:69], v[22:23], 0, s[34:35]
	global_load_dwordx4 v[112:115], v[22:23], off offset:-2048 nt
	global_load_dwordx4 v[116:119], v[22:23], off offset:-1024 nt
	global_load_dwordx4 v[120:123], v[22:23], off nt
	global_load_dwordx4 v[124:127], v[22:23], off offset:1024 nt
	v_lshl_add_u64 v[70:71], v[68:69], 0, s[34:35]
	global_load_dwordx4 v[128:131], v[68:69], off offset:-2048 nt
	global_load_dwordx4 v[132:135], v[68:69], off offset:-1024 nt
	global_load_dwordx4 v[136:139], v[68:69], off nt
	global_load_dwordx4 v[140:143], v[68:69], off offset:1024 nt
	v_lshl_add_u64 v[10:11], v[70:71], 0, s[34:35]
	global_load_dwordx4 v[160:163], v[70:71], off offset:-2048 nt
	global_load_dwordx4 v[164:167], v[70:71], off offset:-1024 nt
	global_load_dwordx4 v[168:171], v[70:71], off nt
	global_load_dwordx4 v[172:175], v[70:71], off offset:1024 nt
	v_lshl_add_u64 v[22:23], v[10:11], 0, s[34:35]
	global_load_dwordx4 v[176:179], v[10:11], off offset:-2048 nt
	global_load_dwordx4 v[180:183], v[10:11], off offset:-1024 nt
	global_load_dwordx4 v[184:187], v[10:11], off nt
	global_load_dwordx4 v[188:191], v[10:11], off offset:1024 nt
	v_lshl_add_u64 v[68:69], v[22:23], 0, s[34:35]
	global_load_dwordx4 v[214:217], v[22:23], off offset:-2048 nt
	global_load_dwordx4 v[218:221], v[22:23], off offset:-1024 nt
	global_load_dwordx4 v[222:225], v[22:23], off nt
	global_load_dwordx4 v[226:229], v[22:23], off offset:1024 nt
	v_lshl_add_u64 v[70:71], v[68:69], 0, s[34:35]
	global_load_dwordx4 v[76:79], v[68:69], off offset:-2048 nt
	global_load_dwordx4 v[80:83], v[68:69], off offset:-1024 nt
	global_load_dwordx4 v[84:87], v[68:69], off nt
	global_load_dwordx4 v[88:91], v[68:69], off offset:1024 nt
	global_load_dwordx4 v[144:147], v[70:71], off offset:-2048 nt
	global_load_dwordx4 v[148:151], v[70:71], off offset:-1024 nt
	global_load_dwordx4 v[152:155], v[70:71], off nt
	global_load_dwordx4 v[230:233], v[70:71], off offset:1024 nt
	s_waitcnt vmcnt(16)
	v_add_f32_e32 v24, 1.0, v24
	v_add_f32_e32 v25, 1.0, v25
	v_add_f32_e32 v26, 1.0, v26
	v_add_f32_e32 v27, 1.0, v27
	v_add_f32_e32 v28, 1.0, v28
	v_add_f32_e32 v29, 1.0, v29
	v_add_f32_e32 v30, 1.0, v30
	v_add_f32_e32 v31, 1.0, v31
	v_add_f32_e32 v32, 1.0, v32
	v_add_f32_e32 v33, 1.0, v33
	v_add_f32_e32 v34, 1.0, v34
	v_add_f32_e32 v35, 1.0, v35
	v_add_f32_e32 v36, 1.0, v36
	v_add_f32_e32 v37, 1.0, v37
	v_add_f32_e32 v38, 1.0, v38
	v_add_f32_e32 v39, 1.0, v39
	v_mul_f32_e32 v4, v96, v96
	v_fmac_f32_e32 v4, v97, v97
	v_fmac_f32_e32 v4, v98, v98
	v_fmac_f32_e32 v4, v99, v99
	v_fmac_f32_e32 v4, v100, v100
	v_fmac_f32_e32 v4, v101, v101
	v_fmac_f32_e32 v4, v102, v102
	v_fmac_f32_e32 v4, v103, v103
	v_fmac_f32_e32 v4, v104, v104
	v_fmac_f32_e32 v4, v105, v105
	v_fmac_f32_e32 v4, v106, v106
	v_fmac_f32_e32 v4, v107, v107
	v_fmac_f32_e32 v4, v108, v108
	v_fmac_f32_e32 v4, v109, v109
	v_fmac_f32_e32 v4, v110, v110
	v_fmac_f32_e32 v4, v111, v111
	v_mul_f32_e32 v5, v112, v112
	v_fmac_f32_e32 v5, v113, v113
	v_fmac_f32_e32 v5, v114, v114
	v_fmac_f32_e32 v5, v115, v115
	v_fmac_f32_e32 v5, v116, v116
	v_fmac_f32_e32 v5, v117, v117
	v_fmac_f32_e32 v5, v118, v118
	v_fmac_f32_e32 v5, v119, v119
	v_fmac_f32_e32 v5, v120, v120
	v_fmac_f32_e32 v5, v121, v121
	v_fmac_f32_e32 v5, v122, v122
	v_fmac_f32_e32 v5, v123, v123
	v_fmac_f32_e32 v5, v124, v124
	v_fmac_f32_e32 v5, v125, v125
	v_fmac_f32_e32 v5, v126, v126
	v_fmac_f32_e32 v5, v127, v127
	v_mul_f32_e32 v6, v128, v128
	v_fmac_f32_e32 v6, v129, v129
	v_fmac_f32_e32 v6, v130, v130
	v_fmac_f32_e32 v6, v131, v131
	v_fmac_f32_e32 v6, v132, v132
	v_fmac_f32_e32 v6, v133, v133
	v_fmac_f32_e32 v6, v134, v134
	v_fmac_f32_e32 v6, v135, v135
	v_fmac_f32_e32 v6, v136, v136
	v_fmac_f32_e32 v6, v137, v137
	v_fmac_f32_e32 v6, v138, v138
	v_fmac_f32_e32 v6, v139, v139
	v_fmac_f32_e32 v6, v140, v140
	v_fmac_f32_e32 v6, v141, v141
	v_fmac_f32_e32 v6, v142, v142
	v_fmac_f32_e32 v6, v143, v143
	v_mul_f32_e32 v7, v160, v160
	v_fmac_f32_e32 v7, v161, v161
	v_fmac_f32_e32 v7, v162, v162
	v_fmac_f32_e32 v7, v163, v163
	v_fmac_f32_e32 v7, v164, v164
	v_fmac_f32_e32 v7, v165, v165
	v_fmac_f32_e32 v7, v166, v166
	v_fmac_f32_e32 v7, v167, v167
	v_fmac_f32_e32 v7, v168, v168
	v_fmac_f32_e32 v7, v169, v169
	v_fmac_f32_e32 v7, v170, v170
	v_fmac_f32_e32 v7, v171, v171
	v_fmac_f32_e32 v7, v172, v172
	v_fmac_f32_e32 v7, v173, v173
	v_fmac_f32_e32 v7, v174, v174
	v_fmac_f32_e32 v7, v175, v175
	ds_bpermute_b32 v8, v15, v4
	ds_bpermute_b32 v9, v15, v5
	ds_bpermute_b32 v14, v15, v6
	ds_bpermute_b32 v21, v15, v7
	s_waitcnt lgkmcnt(3)
	v_add_f32_e32 v4, v4, v8
	s_waitcnt lgkmcnt(2)
	v_add_f32_e32 v5, v5, v9
	s_waitcnt lgkmcnt(1)
	v_add_f32_e32 v6, v6, v14
	s_waitcnt lgkmcnt(0)
	v_add_f32_e32 v7, v7, v21
	ds_bpermute_b32 v8, v16, v4
	ds_bpermute_b32 v9, v16, v5
	ds_bpermute_b32 v14, v16, v6
	ds_bpermute_b32 v21, v16, v7
	s_waitcnt lgkmcnt(3)
	v_add_f32_e32 v4, v4, v8
	s_waitcnt lgkmcnt(2)
	v_add_f32_e32 v5, v5, v9
	s_waitcnt lgkmcnt(1)
	v_add_f32_e32 v6, v6, v14
	s_waitcnt lgkmcnt(0)
	v_add_f32_e32 v7, v7, v21
	ds_bpermute_b32 v8, v17, v4
	ds_bpermute_b32 v9, v17, v5
	ds_bpermute_b32 v14, v17, v6
	ds_bpermute_b32 v21, v17, v7
	s_waitcnt lgkmcnt(3)
	v_add_f32_e32 v4, v4, v8
	s_waitcnt lgkmcnt(2)
	v_add_f32_e32 v5, v5, v9
	s_waitcnt lgkmcnt(1)
	v_add_f32_e32 v6, v6, v14
	s_waitcnt lgkmcnt(0)
	v_add_f32_e32 v7, v7, v21
	ds_bpermute_b32 v8, v18, v4
	ds_bpermute_b32 v9, v18, v5
	ds_bpermute_b32 v14, v18, v6
	ds_bpermute_b32 v21, v18, v7
	s_waitcnt lgkmcnt(3)
	v_add_f32_e32 v4, v4, v8
	s_waitcnt lgkmcnt(2)
	v_add_f32_e32 v5, v5, v9
	s_waitcnt lgkmcnt(1)
	v_add_f32_e32 v6, v6, v14
	s_waitcnt lgkmcnt(0)
	v_add_f32_e32 v7, v7, v21
	ds_bpermute_b32 v8, v19, v4
	ds_bpermute_b32 v9, v19, v5
	ds_bpermute_b32 v14, v19, v6
	ds_bpermute_b32 v21, v19, v7
	s_waitcnt lgkmcnt(3)
	v_add_f32_e32 v4, v4, v8
	s_waitcnt lgkmcnt(2)
	v_add_f32_e32 v5, v5, v9
	s_waitcnt lgkmcnt(1)
	v_add_f32_e32 v6, v6, v14
	s_waitcnt lgkmcnt(0)
	v_add_f32_e32 v7, v7, v21
	ds_bpermute_b32 v8, v20, v4
	ds_bpermute_b32 v9, v20, v5
	ds_bpermute_b32 v14, v20, v6
	ds_bpermute_b32 v21, v20, v7
	s_waitcnt lgkmcnt(3)
	v_add_f32_e32 v4, v4, v8
	s_waitcnt lgkmcnt(2)
	v_add_f32_e32 v5, v5, v9
	s_waitcnt lgkmcnt(1)
	v_add_f32_e32 v6, v6, v14
	s_waitcnt lgkmcnt(0)
	v_add_f32_e32 v7, v7, v21
	v_fmamk_f32 v4, v4, 0x3a800000, v200
	v_mul_f32_e32 v8, 0x4b800000, v4
	v_cmp_gt_f32_e32 vcc, 0x800000, v4
	s_nop 1
	v_cndmask_b32_e32 v4, v4, v8, vcc
	v_rsq_f32_e32 v4, v4
	s_nop 0
	v_mul_f32_e32 v8, 0x45800000, v4
	v_cndmask_b32_e32 v4, v4, v8, vcc
	v_fmamk_f32 v5, v5, 0x3a800000, v200
	v_mul_f32_e32 v9, 0x4b800000, v5
	v_cmp_gt_f32_e32 vcc, 0x800000, v5
	s_nop 1
	v_cndmask_b32_e32 v5, v5, v9, vcc
	v_rsq_f32_e32 v5, v5
	s_nop 0
	v_mul_f32_e32 v9, 0x45800000, v5
	v_cndmask_b32_e32 v5, v5, v9, vcc
	v_fmamk_f32 v6, v6, 0x3a800000, v200
	v_mul_f32_e32 v14, 0x4b800000, v6
	v_cmp_gt_f32_e32 vcc, 0x800000, v6
	s_nop 1
	v_cndmask_b32_e32 v6, v6, v14, vcc
	v_rsq_f32_e32 v6, v6
	s_nop 0
	v_mul_f32_e32 v14, 0x45800000, v6
	v_cndmask_b32_e32 v6, v6, v14, vcc
	v_fmamk_f32 v7, v7, 0x3a800000, v200
	v_mul_f32_e32 v21, 0x4b800000, v7
	v_cmp_gt_f32_e32 vcc, 0x800000, v7
	s_nop 1
	v_cndmask_b32_e32 v7, v7, v21, vcc
	v_rsq_f32_e32 v7, v7
	s_nop 0
	v_mul_f32_e32 v21, 0x45800000, v7
	v_cndmask_b32_e32 v7, v7, v21, vcc
	v_mul_f32_e32 v96, v96, v4
	v_mul_f32_e32 v97, v97, v4
	v_mul_f32_e32 v98, v98, v4
	v_mul_f32_e32 v99, v99, v4
	v_mul_f32_e32 v96, v0, v96
	v_mul_f32_e32 v97, v1, v97
	v_mul_f32_e32 v98, v2, v98
	v_mul_f32_e32 v99, v3, v99
	v_fma_f32 v96, v24, v96, v52
	v_fma_f32 v97, v25, v97, v53
	v_fma_f32 v98, v26, v98, v54
	v_fma_f32 v99, v27, v99, v55
	v_cvt_pk_bf16_f32 v96, v96, v97
	v_cvt_pk_bf16_f32 v97, v98, v99
	global_store_dwordx2 v[12:13], v[96:97], off offset:-1024
	v_mul_f32_e32 v100, v100, v4
	v_mul_f32_e32 v101, v101, v4
	v_mul_f32_e32 v102, v102, v4
	v_mul_f32_e32 v103, v103, v4
	v_mul_f32_e32 v100, v40, v100
	v_mul_f32_e32 v101, v41, v101
	v_mul_f32_e32 v102, v42, v102
	v_mul_f32_e32 v103, v43, v103
	v_fma_f32 v100, v28, v100, v56
	v_fma_f32 v101, v29, v101, v57
	v_fma_f32 v102, v30, v102, v58
	v_fma_f32 v103, v31, v103, v59
	v_cvt_pk_bf16_f32 v100, v100, v101
	v_cvt_pk_bf16_f32 v101, v102, v103
	global_store_dwordx2 v[12:13], v[100:101], off offset:-512
	v_mul_f32_e32 v104, v104, v4
	v_mul_f32_e32 v105, v105, v4
	v_mul_f32_e32 v106, v106, v4
	v_mul_f32_e32 v107, v107, v4
	v_mul_f32_e32 v104, v44, v104
	v_mul_f32_e32 v105, v45, v105
	v_mul_f32_e32 v106, v46, v106
	v_mul_f32_e32 v107, v47, v107
	v_fma_f32 v104, v32, v104, v60
	v_fma_f32 v105, v33, v105, v61
	v_fma_f32 v106, v34, v106, v62
	v_fma_f32 v107, v35, v107, v63
	v_cvt_pk_bf16_f32 v104, v104, v105
	v_cvt_pk_bf16_f32 v105, v106, v107
	global_store_dwordx2 v[12:13], v[104:105], off
	v_mul_f32_e32 v108, v108, v4
	v_mul_f32_e32 v109, v109, v4
	v_mul_f32_e32 v110, v110, v4
	v_mul_f32_e32 v111, v111, v4
	v_mul_f32_e32 v108, v48, v108
	v_mul_f32_e32 v109, v49, v109
	v_mul_f32_e32 v110, v50, v110
	v_mul_f32_e32 v111, v51, v111
	v_fma_f32 v108, v36, v108, v64
	v_fma_f32 v109, v37, v109, v65
	v_fma_f32 v110, v38, v110, v66
	v_fma_f32 v111, v39, v111, v67
	v_cvt_pk_bf16_f32 v108, v108, v109
	v_cvt_pk_bf16_f32 v109, v110, v111
	global_store_dwordx2 v[12:13], v[108:109], off offset:512
	v_lshl_add_u64 v[12:13], v[12:13], 0, s[40:41]
	v_mul_f32_e32 v112, v112, v5
	v_mul_f32_e32 v113, v113, v5
	v_mul_f32_e32 v114, v114, v5
	v_mul_f32_e32 v115, v115, v5
	v_mul_f32_e32 v112, v0, v112
	v_mul_f32_e32 v113, v1, v113
	v_mul_f32_e32 v114, v2, v114
	v_mul_f32_e32 v115, v3, v115
	v_fma_f32 v112, v24, v112, v52
	v_fma_f32 v113, v25, v113, v53
	v_fma_f32 v114, v26, v114, v54
	v_fma_f32 v115, v27, v115, v55
	v_cvt_pk_bf16_f32 v112, v112, v113
	v_cvt_pk_bf16_f32 v113, v114, v115
	global_store_dwordx2 v[12:13], v[112:113], off offset:-1024
	v_mul_f32_e32 v116, v116, v5
	v_mul_f32_e32 v117, v117, v5
	v_mul_f32_e32 v118, v118, v5
	v_mul_f32_e32 v119, v119, v5
	v_mul_f32_e32 v116, v40, v116
	v_mul_f32_e32 v117, v41, v117
	v_mul_f32_e32 v118, v42, v118
	v_mul_f32_e32 v119, v43, v119
	v_fma_f32 v116, v28, v116, v56
	v_fma_f32 v117, v29, v117, v57
	v_fma_f32 v118, v30, v118, v58
	v_fma_f32 v119, v31, v119, v59
	v_cvt_pk_bf16_f32 v116, v116, v117
	v_cvt_pk_bf16_f32 v117, v118, v119
	global_store_dwordx2 v[12:13], v[116:117], off offset:-512
	v_mul_f32_e32 v120, v120, v5
	v_mul_f32_e32 v121, v121, v5
	v_mul_f32_e32 v122, v122, v5
	v_mul_f32_e32 v123, v123, v5
	v_mul_f32_e32 v120, v44, v120
	v_mul_f32_e32 v121, v45, v121
	v_mul_f32_e32 v122, v46, v122
	v_mul_f32_e32 v123, v47, v123
	v_fma_f32 v120, v32, v120, v60
	v_fma_f32 v121, v33, v121, v61
	v_fma_f32 v122, v34, v122, v62
	v_fma_f32 v123, v35, v123, v63
	v_cvt_pk_bf16_f32 v120, v120, v121
	v_cvt_pk_bf16_f32 v121, v122, v123
	global_store_dwordx2 v[12:13], v[120:121], off
	v_mul_f32_e32 v124, v124, v5
	v_mul_f32_e32 v125, v125, v5
	v_mul_f32_e32 v126, v126, v5
	v_mul_f32_e32 v127, v127, v5
	v_mul_f32_e32 v124, v48, v124
	v_mul_f32_e32 v125, v49, v125
	v_mul_f32_e32 v126, v50, v126
	v_mul_f32_e32 v127, v51, v127
	v_fma_f32 v124, v36, v124, v64
	v_fma_f32 v125, v37, v125, v65
	v_fma_f32 v126, v38, v126, v66
	v_fma_f32 v127, v39, v127, v67
	v_cvt_pk_bf16_f32 v124, v124, v125
	v_cvt_pk_bf16_f32 v125, v126, v127
	global_store_dwordx2 v[12:13], v[124:125], off offset:512
	v_lshl_add_u64 v[12:13], v[12:13], 0, s[40:41]
	v_mul_f32_e32 v128, v128, v6
	v_mul_f32_e32 v129, v129, v6
	v_mul_f32_e32 v130, v130, v6
	v_mul_f32_e32 v131, v131, v6
	v_mul_f32_e32 v128, v0, v128
	v_mul_f32_e32 v129, v1, v129
	v_mul_f32_e32 v130, v2, v130
	v_mul_f32_e32 v131, v3, v131
	v_fma_f32 v128, v24, v128, v52
	v_fma_f32 v129, v25, v129, v53
	v_fma_f32 v130, v26, v130, v54
	v_fma_f32 v131, v27, v131, v55
	v_cvt_pk_bf16_f32 v128, v128, v129
	v_cvt_pk_bf16_f32 v129, v130, v131
	global_store_dwordx2 v[12:13], v[128:129], off offset:-1024
	v_mul_f32_e32 v132, v132, v6
	v_mul_f32_e32 v133, v133, v6
	v_mul_f32_e32 v134, v134, v6
	v_mul_f32_e32 v135, v135, v6
	v_mul_f32_e32 v132, v40, v132
	v_mul_f32_e32 v133, v41, v133
	v_mul_f32_e32 v134, v42, v134
	v_mul_f32_e32 v135, v43, v135
	v_fma_f32 v132, v28, v132, v56
	v_fma_f32 v133, v29, v133, v57
	v_fma_f32 v134, v30, v134, v58
	v_fma_f32 v135, v31, v135, v59
	v_cvt_pk_bf16_f32 v132, v132, v133
	v_cvt_pk_bf16_f32 v133, v134, v135
	global_store_dwordx2 v[12:13], v[132:133], off offset:-512
	v_mul_f32_e32 v136, v136, v6
	v_mul_f32_e32 v137, v137, v6
	v_mul_f32_e32 v138, v138, v6
	v_mul_f32_e32 v139, v139, v6
	v_mul_f32_e32 v136, v44, v136
	v_mul_f32_e32 v137, v45, v137
	v_mul_f32_e32 v138, v46, v138
	v_mul_f32_e32 v139, v47, v139
	v_fma_f32 v136, v32, v136, v60
	v_fma_f32 v137, v33, v137, v61
	v_fma_f32 v138, v34, v138, v62
	v_fma_f32 v139, v35, v139, v63
	v_cvt_pk_bf16_f32 v136, v136, v137
	v_cvt_pk_bf16_f32 v137, v138, v139
	global_store_dwordx2 v[12:13], v[136:137], off
	v_mul_f32_e32 v140, v140, v6
	v_mul_f32_e32 v141, v141, v6
	v_mul_f32_e32 v142, v142, v6
	v_mul_f32_e32 v143, v143, v6
	v_mul_f32_e32 v140, v48, v140
	v_mul_f32_e32 v141, v49, v141
	v_mul_f32_e32 v142, v50, v142
	v_mul_f32_e32 v143, v51, v143
	v_fma_f32 v140, v36, v140, v64
	v_fma_f32 v141, v37, v141, v65
	v_fma_f32 v142, v38, v142, v66
	v_fma_f32 v143, v39, v143, v67
	v_cvt_pk_bf16_f32 v140, v140, v141
	v_cvt_pk_bf16_f32 v141, v142, v143
	global_store_dwordx2 v[12:13], v[140:141], off offset:512
	v_lshl_add_u64 v[12:13], v[12:13], 0, s[40:41]
	v_mul_f32_e32 v160, v160, v7
	v_mul_f32_e32 v161, v161, v7
	v_mul_f32_e32 v162, v162, v7
	v_mul_f32_e32 v163, v163, v7
	v_mul_f32_e32 v160, v0, v160
	v_mul_f32_e32 v161, v1, v161
	v_mul_f32_e32 v162, v2, v162
	v_mul_f32_e32 v163, v3, v163
	v_fma_f32 v160, v24, v160, v52
	v_fma_f32 v161, v25, v161, v53
	v_fma_f32 v162, v26, v162, v54
	v_fma_f32 v163, v27, v163, v55
	v_cvt_pk_bf16_f32 v160, v160, v161
	v_cvt_pk_bf16_f32 v161, v162, v163
	global_store_dwordx2 v[12:13], v[160:161], off offset:-1024
	v_mul_f32_e32 v164, v164, v7
	v_mul_f32_e32 v165, v165, v7
	v_mul_f32_e32 v166, v166, v7
	v_mul_f32_e32 v167, v167, v7
	v_mul_f32_e32 v164, v40, v164
	v_mul_f32_e32 v165, v41, v165
	v_mul_f32_e32 v166, v42, v166
	v_mul_f32_e32 v167, v43, v167
	v_fma_f32 v164, v28, v164, v56
	v_fma_f32 v165, v29, v165, v57
	v_fma_f32 v166, v30, v166, v58
	v_fma_f32 v167, v31, v167, v59
	v_cvt_pk_bf16_f32 v164, v164, v165
	v_cvt_pk_bf16_f32 v165, v166, v167
	global_store_dwordx2 v[12:13], v[164:165], off offset:-512
	v_mul_f32_e32 v168, v168, v7
	v_mul_f32_e32 v169, v169, v7
	v_mul_f32_e32 v170, v170, v7
	v_mul_f32_e32 v171, v171, v7
	v_mul_f32_e32 v168, v44, v168
	v_mul_f32_e32 v169, v45, v169
	v_mul_f32_e32 v170, v46, v170
	v_mul_f32_e32 v171, v47, v171
	v_fma_f32 v168, v32, v168, v60
	v_fma_f32 v169, v33, v169, v61
	v_fma_f32 v170, v34, v170, v62
	v_fma_f32 v171, v35, v171, v63
	v_cvt_pk_bf16_f32 v168, v168, v169
	v_cvt_pk_bf16_f32 v169, v170, v171
	global_store_dwordx2 v[12:13], v[168:169], off
	v_mul_f32_e32 v172, v172, v7
	v_mul_f32_e32 v173, v173, v7
	v_mul_f32_e32 v174, v174, v7
	v_mul_f32_e32 v175, v175, v7
	v_mul_f32_e32 v172, v48, v172
	v_mul_f32_e32 v173, v49, v173
	v_mul_f32_e32 v174, v50, v174
	v_mul_f32_e32 v175, v51, v175
	v_fma_f32 v172, v36, v172, v64
	v_fma_f32 v173, v37, v173, v65
	v_fma_f32 v174, v38, v174, v66
	v_fma_f32 v175, v39, v175, v67
	v_cvt_pk_bf16_f32 v172, v172, v173
	v_cvt_pk_bf16_f32 v173, v174, v175
	global_store_dwordx2 v[12:13], v[172:173], off offset:512
	v_lshl_add_u64 v[12:13], v[12:13], 0, s[40:41]
	s_waitcnt vmcnt(16)
	v_mul_f32_e32 v4, v176, v176
	v_fmac_f32_e32 v4, v177, v177
	v_fmac_f32_e32 v4, v178, v178
	v_fmac_f32_e32 v4, v179, v179
	v_fmac_f32_e32 v4, v180, v180
	v_fmac_f32_e32 v4, v181, v181
	v_fmac_f32_e32 v4, v182, v182
	v_fmac_f32_e32 v4, v183, v183
	v_fmac_f32_e32 v4, v184, v184
	v_fmac_f32_e32 v4, v185, v185
	v_fmac_f32_e32 v4, v186, v186
	v_fmac_f32_e32 v4, v187, v187
	v_fmac_f32_e32 v4, v188, v188
	v_fmac_f32_e32 v4, v189, v189
	v_fmac_f32_e32 v4, v190, v190
	v_fmac_f32_e32 v4, v191, v191
	v_mul_f32_e32 v5, v214, v214
	v_fmac_f32_e32 v5, v215, v215
	v_fmac_f32_e32 v5, v216, v216
	v_fmac_f32_e32 v5, v217, v217
	v_fmac_f32_e32 v5, v218, v218
	v_fmac_f32_e32 v5, v219, v219
	v_fmac_f32_e32 v5, v220, v220
	v_fmac_f32_e32 v5, v221, v221
	v_fmac_f32_e32 v5, v222, v222
	v_fmac_f32_e32 v5, v223, v223
	v_fmac_f32_e32 v5, v224, v224
	v_fmac_f32_e32 v5, v225, v225
	v_fmac_f32_e32 v5, v226, v226
	v_fmac_f32_e32 v5, v227, v227
	v_fmac_f32_e32 v5, v228, v228
	v_fmac_f32_e32 v5, v229, v229
	v_mul_f32_e32 v6, v76, v76
	v_fmac_f32_e32 v6, v77, v77
	v_fmac_f32_e32 v6, v78, v78
	v_fmac_f32_e32 v6, v79, v79
	v_fmac_f32_e32 v6, v80, v80
	v_fmac_f32_e32 v6, v81, v81
	v_fmac_f32_e32 v6, v82, v82
	v_fmac_f32_e32 v6, v83, v83
	v_fmac_f32_e32 v6, v84, v84
	v_fmac_f32_e32 v6, v85, v85
	v_fmac_f32_e32 v6, v86, v86
	v_fmac_f32_e32 v6, v87, v87
	v_fmac_f32_e32 v6, v88, v88
	v_fmac_f32_e32 v6, v89, v89
	v_fmac_f32_e32 v6, v90, v90
	v_fmac_f32_e32 v6, v91, v91
	v_mul_f32_e32 v7, v144, v144
	v_fmac_f32_e32 v7, v145, v145
	v_fmac_f32_e32 v7, v146, v146
	v_fmac_f32_e32 v7, v147, v147
	v_fmac_f32_e32 v7, v148, v148
	v_fmac_f32_e32 v7, v149, v149
	v_fmac_f32_e32 v7, v150, v150
	v_fmac_f32_e32 v7, v151, v151
	v_fmac_f32_e32 v7, v152, v152
	v_fmac_f32_e32 v7, v153, v153
	v_fmac_f32_e32 v7, v154, v154
	v_fmac_f32_e32 v7, v155, v155
	v_fmac_f32_e32 v7, v230, v230
	v_fmac_f32_e32 v7, v231, v231
	v_fmac_f32_e32 v7, v232, v232
	v_fmac_f32_e32 v7, v233, v233
	ds_bpermute_b32 v8, v15, v4
	ds_bpermute_b32 v9, v15, v5
	ds_bpermute_b32 v14, v15, v6
	ds_bpermute_b32 v21, v15, v7
	s_waitcnt lgkmcnt(3)
	v_add_f32_e32 v4, v4, v8
	s_waitcnt lgkmcnt(2)
	v_add_f32_e32 v5, v5, v9
	s_waitcnt lgkmcnt(1)
	v_add_f32_e32 v6, v6, v14
	s_waitcnt lgkmcnt(0)
	v_add_f32_e32 v7, v7, v21
	ds_bpermute_b32 v8, v16, v4
	ds_bpermute_b32 v9, v16, v5
	ds_bpermute_b32 v14, v16, v6
	ds_bpermute_b32 v21, v16, v7
	s_waitcnt lgkmcnt(3)
	v_add_f32_e32 v4, v4, v8
	s_waitcnt lgkmcnt(2)
	v_add_f32_e32 v5, v5, v9
	s_waitcnt lgkmcnt(1)
	v_add_f32_e32 v6, v6, v14
	s_waitcnt lgkmcnt(0)
	v_add_f32_e32 v7, v7, v21
	ds_bpermute_b32 v8, v17, v4
	ds_bpermute_b32 v9, v17, v5
	ds_bpermute_b32 v14, v17, v6
	ds_bpermute_b32 v21, v17, v7
	s_waitcnt lgkmcnt(3)
	v_add_f32_e32 v4, v4, v8
	s_waitcnt lgkmcnt(2)
	v_add_f32_e32 v5, v5, v9
	s_waitcnt lgkmcnt(1)
	v_add_f32_e32 v6, v6, v14
	s_waitcnt lgkmcnt(0)
	v_add_f32_e32 v7, v7, v21
	ds_bpermute_b32 v8, v18, v4
	ds_bpermute_b32 v9, v18, v5
	ds_bpermute_b32 v14, v18, v6
	ds_bpermute_b32 v21, v18, v7
	s_waitcnt lgkmcnt(3)
	v_add_f32_e32 v4, v4, v8
	s_waitcnt lgkmcnt(2)
	v_add_f32_e32 v5, v5, v9
	s_waitcnt lgkmcnt(1)
	v_add_f32_e32 v6, v6, v14
	s_waitcnt lgkmcnt(0)
	v_add_f32_e32 v7, v7, v21
	ds_bpermute_b32 v8, v19, v4
	ds_bpermute_b32 v9, v19, v5
	ds_bpermute_b32 v14, v19, v6
	ds_bpermute_b32 v21, v19, v7
	s_waitcnt lgkmcnt(3)
	v_add_f32_e32 v4, v4, v8
	s_waitcnt lgkmcnt(2)
	v_add_f32_e32 v5, v5, v9
	s_waitcnt lgkmcnt(1)
	v_add_f32_e32 v6, v6, v14
	s_waitcnt lgkmcnt(0)
	v_add_f32_e32 v7, v7, v21
	ds_bpermute_b32 v8, v20, v4
	ds_bpermute_b32 v9, v20, v5
	ds_bpermute_b32 v14, v20, v6
	ds_bpermute_b32 v21, v20, v7
	s_waitcnt lgkmcnt(3)
	v_add_f32_e32 v4, v4, v8
	s_waitcnt lgkmcnt(2)
	v_add_f32_e32 v5, v5, v9
	s_waitcnt lgkmcnt(1)
	v_add_f32_e32 v6, v6, v14
	s_waitcnt lgkmcnt(0)
	v_add_f32_e32 v7, v7, v21
	v_fmamk_f32 v4, v4, 0x3a800000, v200
	v_mul_f32_e32 v8, 0x4b800000, v4
	v_cmp_gt_f32_e32 vcc, 0x800000, v4
	s_nop 1
	v_cndmask_b32_e32 v4, v4, v8, vcc
	v_rsq_f32_e32 v4, v4
	s_nop 0
	v_mul_f32_e32 v8, 0x45800000, v4
	v_cndmask_b32_e32 v4, v4, v8, vcc
	v_fmamk_f32 v5, v5, 0x3a800000, v200
	v_mul_f32_e32 v9, 0x4b800000, v5
	v_cmp_gt_f32_e32 vcc, 0x800000, v5
	s_nop 1
	v_cndmask_b32_e32 v5, v5, v9, vcc
	v_rsq_f32_e32 v5, v5
	s_nop 0
	v_mul_f32_e32 v9, 0x45800000, v5
	v_cndmask_b32_e32 v5, v5, v9, vcc
	v_fmamk_f32 v6, v6, 0x3a800000, v200
	v_mul_f32_e32 v14, 0x4b800000, v6
	v_cmp_gt_f32_e32 vcc, 0x800000, v6
	s_nop 1
	v_cndmask_b32_e32 v6, v6, v14, vcc
	v_rsq_f32_e32 v6, v6
	s_nop 0
	v_mul_f32_e32 v14, 0x45800000, v6
	v_cndmask_b32_e32 v6, v6, v14, vcc
	v_fmamk_f32 v7, v7, 0x3a800000, v200
	v_mul_f32_e32 v21, 0x4b800000, v7
	v_cmp_gt_f32_e32 vcc, 0x800000, v7
	s_nop 1
	v_cndmask_b32_e32 v7, v7, v21, vcc
	v_rsq_f32_e32 v7, v7
	s_nop 0
	v_mul_f32_e32 v21, 0x45800000, v7
	v_cndmask_b32_e32 v7, v7, v21, vcc
	v_mul_f32_e32 v176, v176, v4
	v_mul_f32_e32 v177, v177, v4
	v_mul_f32_e32 v178, v178, v4
	v_mul_f32_e32 v179, v179, v4
	v_mul_f32_e32 v176, v0, v176
	v_mul_f32_e32 v177, v1, v177
	v_mul_f32_e32 v178, v2, v178
	v_mul_f32_e32 v179, v3, v179
	v_fma_f32 v176, v24, v176, v52
	v_fma_f32 v177, v25, v177, v53
	v_fma_f32 v178, v26, v178, v54
	v_fma_f32 v179, v27, v179, v55
	v_cvt_pk_bf16_f32 v176, v176, v177
	v_cvt_pk_bf16_f32 v177, v178, v179
	global_store_dwordx2 v[12:13], v[176:177], off offset:-1024
	v_mul_f32_e32 v180, v180, v4
	v_mul_f32_e32 v181, v181, v4
	v_mul_f32_e32 v182, v182, v4
	v_mul_f32_e32 v183, v183, v4
	v_mul_f32_e32 v180, v40, v180
	v_mul_f32_e32 v181, v41, v181
	v_mul_f32_e32 v182, v42, v182
	v_mul_f32_e32 v183, v43, v183
	v_fma_f32 v180, v28, v180, v56
	v_fma_f32 v181, v29, v181, v57
	v_fma_f32 v182, v30, v182, v58
	v_fma_f32 v183, v31, v183, v59
	v_cvt_pk_bf16_f32 v180, v180, v181
	v_cvt_pk_bf16_f32 v181, v182, v183
	global_store_dwordx2 v[12:13], v[180:181], off offset:-512
	v_mul_f32_e32 v184, v184, v4
	v_mul_f32_e32 v185, v185, v4
	v_mul_f32_e32 v186, v186, v4
	v_mul_f32_e32 v187, v187, v4
	v_mul_f32_e32 v184, v44, v184
	v_mul_f32_e32 v185, v45, v185
	v_mul_f32_e32 v186, v46, v186
	v_mul_f32_e32 v187, v47, v187
	v_fma_f32 v184, v32, v184, v60
	v_fma_f32 v185, v33, v185, v61
	v_fma_f32 v186, v34, v186, v62
	v_fma_f32 v187, v35, v187, v63
	v_cvt_pk_bf16_f32 v184, v184, v185
	v_cvt_pk_bf16_f32 v185, v186, v187
	global_store_dwordx2 v[12:13], v[184:185], off
	v_mul_f32_e32 v188, v188, v4
	v_mul_f32_e32 v189, v189, v4
	v_mul_f32_e32 v190, v190, v4
	v_mul_f32_e32 v191, v191, v4
	v_mul_f32_e32 v188, v48, v188
	v_mul_f32_e32 v189, v49, v189
	v_mul_f32_e32 v190, v50, v190
	v_mul_f32_e32 v191, v51, v191
	v_fma_f32 v188, v36, v188, v64
	v_fma_f32 v189, v37, v189, v65
	v_fma_f32 v190, v38, v190, v66
	v_fma_f32 v191, v39, v191, v67
	v_cvt_pk_bf16_f32 v188, v188, v189
	v_cvt_pk_bf16_f32 v189, v190, v191
	global_store_dwordx2 v[12:13], v[188:189], off offset:512
	v_lshl_add_u64 v[12:13], v[12:13], 0, s[40:41]
	v_mul_f32_e32 v214, v214, v5
	v_mul_f32_e32 v215, v215, v5
	v_mul_f32_e32 v216, v216, v5
	v_mul_f32_e32 v217, v217, v5
	v_mul_f32_e32 v214, v0, v214
	v_mul_f32_e32 v215, v1, v215
	v_mul_f32_e32 v216, v2, v216
	v_mul_f32_e32 v217, v3, v217
	v_fma_f32 v214, v24, v214, v52
	v_fma_f32 v215, v25, v215, v53
	v_fma_f32 v216, v26, v216, v54
	v_fma_f32 v217, v27, v217, v55
	v_cvt_pk_bf16_f32 v214, v214, v215
	v_cvt_pk_bf16_f32 v215, v216, v217
	global_store_dwordx2 v[12:13], v[214:215], off offset:-1024
	v_mul_f32_e32 v218, v218, v5
	v_mul_f32_e32 v219, v219, v5
	v_mul_f32_e32 v220, v220, v5
	v_mul_f32_e32 v221, v221, v5
	v_mul_f32_e32 v218, v40, v218
	v_mul_f32_e32 v219, v41, v219
	v_mul_f32_e32 v220, v42, v220
	v_mul_f32_e32 v221, v43, v221
	v_fma_f32 v218, v28, v218, v56
	v_fma_f32 v219, v29, v219, v57
	v_fma_f32 v220, v30, v220, v58
	v_fma_f32 v221, v31, v221, v59
	v_cvt_pk_bf16_f32 v218, v218, v219
	v_cvt_pk_bf16_f32 v219, v220, v221
	global_store_dwordx2 v[12:13], v[218:219], off offset:-512
	v_mul_f32_e32 v222, v222, v5
	v_mul_f32_e32 v223, v223, v5
	v_mul_f32_e32 v224, v224, v5
	v_mul_f32_e32 v225, v225, v5
	v_mul_f32_e32 v222, v44, v222
	v_mul_f32_e32 v223, v45, v223
	v_mul_f32_e32 v224, v46, v224
	v_mul_f32_e32 v225, v47, v225
	v_fma_f32 v222, v32, v222, v60
	v_fma_f32 v223, v33, v223, v61
	v_fma_f32 v224, v34, v224, v62
	v_fma_f32 v225, v35, v225, v63
	v_cvt_pk_bf16_f32 v222, v222, v223
	v_cvt_pk_bf16_f32 v223, v224, v225
	global_store_dwordx2 v[12:13], v[222:223], off
	v_mul_f32_e32 v226, v226, v5
	v_mul_f32_e32 v227, v227, v5
	v_mul_f32_e32 v228, v228, v5
	v_mul_f32_e32 v229, v229, v5
	v_mul_f32_e32 v226, v48, v226
	v_mul_f32_e32 v227, v49, v227
	v_mul_f32_e32 v228, v50, v228
	v_mul_f32_e32 v229, v51, v229
	v_fma_f32 v226, v36, v226, v64
	v_fma_f32 v227, v37, v227, v65
	v_fma_f32 v228, v38, v228, v66
	v_fma_f32 v229, v39, v229, v67
	v_cvt_pk_bf16_f32 v226, v226, v227
	v_cvt_pk_bf16_f32 v227, v228, v229
	global_store_dwordx2 v[12:13], v[226:227], off offset:512
	v_lshl_add_u64 v[12:13], v[12:13], 0, s[40:41]
	v_mul_f32_e32 v76, v76, v6
	v_mul_f32_e32 v77, v77, v6
	v_mul_f32_e32 v78, v78, v6
	v_mul_f32_e32 v79, v79, v6
	v_mul_f32_e32 v76, v0, v76
	v_mul_f32_e32 v77, v1, v77
	v_mul_f32_e32 v78, v2, v78
	v_mul_f32_e32 v79, v3, v79
	v_fma_f32 v76, v24, v76, v52
	v_fma_f32 v77, v25, v77, v53
	v_fma_f32 v78, v26, v78, v54
	v_fma_f32 v79, v27, v79, v55
	v_cvt_pk_bf16_f32 v76, v76, v77
	v_cvt_pk_bf16_f32 v77, v78, v79
	global_store_dwordx2 v[12:13], v[76:77], off offset:-1024
	v_mul_f32_e32 v80, v80, v6
	v_mul_f32_e32 v81, v81, v6
	v_mul_f32_e32 v82, v82, v6
	v_mul_f32_e32 v83, v83, v6
	v_mul_f32_e32 v80, v40, v80
	v_mul_f32_e32 v81, v41, v81
	v_mul_f32_e32 v82, v42, v82
	v_mul_f32_e32 v83, v43, v83
	v_fma_f32 v80, v28, v80, v56
	v_fma_f32 v81, v29, v81, v57
	v_fma_f32 v82, v30, v82, v58
	v_fma_f32 v83, v31, v83, v59
	v_cvt_pk_bf16_f32 v80, v80, v81
	v_cvt_pk_bf16_f32 v81, v82, v83
	global_store_dwordx2 v[12:13], v[80:81], off offset:-512
	v_mul_f32_e32 v84, v84, v6
	v_mul_f32_e32 v85, v85, v6
	v_mul_f32_e32 v86, v86, v6
	v_mul_f32_e32 v87, v87, v6
	v_mul_f32_e32 v84, v44, v84
	v_mul_f32_e32 v85, v45, v85
	v_mul_f32_e32 v86, v46, v86
	v_mul_f32_e32 v87, v47, v87
	v_fma_f32 v84, v32, v84, v60
	v_fma_f32 v85, v33, v85, v61
	v_fma_f32 v86, v34, v86, v62
	v_fma_f32 v87, v35, v87, v63
	v_cvt_pk_bf16_f32 v84, v84, v85
	v_cvt_pk_bf16_f32 v85, v86, v87
	global_store_dwordx2 v[12:13], v[84:85], off
	v_mul_f32_e32 v88, v88, v6
	v_mul_f32_e32 v89, v89, v6
	v_mul_f32_e32 v90, v90, v6
	v_mul_f32_e32 v91, v91, v6
	v_mul_f32_e32 v88, v48, v88
	v_mul_f32_e32 v89, v49, v89
	v_mul_f32_e32 v90, v50, v90
	v_mul_f32_e32 v91, v51, v91
	v_fma_f32 v88, v36, v88, v64
	v_fma_f32 v89, v37, v89, v65
	v_fma_f32 v90, v38, v90, v66
	v_fma_f32 v91, v39, v91, v67
	v_cvt_pk_bf16_f32 v88, v88, v89
	v_cvt_pk_bf16_f32 v89, v90, v91
	global_store_dwordx2 v[12:13], v[88:89], off offset:512
	v_lshl_add_u64 v[12:13], v[12:13], 0, s[40:41]
	v_mul_f32_e32 v144, v144, v7
	v_mul_f32_e32 v145, v145, v7
	v_mul_f32_e32 v146, v146, v7
	v_mul_f32_e32 v147, v147, v7
	v_mul_f32_e32 v144, v0, v144
	v_mul_f32_e32 v145, v1, v145
	v_mul_f32_e32 v146, v2, v146
	v_mul_f32_e32 v147, v3, v147
	v_fma_f32 v144, v24, v144, v52
	v_fma_f32 v145, v25, v145, v53
	v_fma_f32 v146, v26, v146, v54
	v_fma_f32 v147, v27, v147, v55
	v_cvt_pk_bf16_f32 v144, v144, v145
	v_cvt_pk_bf16_f32 v145, v146, v147
	global_store_dwordx2 v[12:13], v[144:145], off offset:-1024
	v_mul_f32_e32 v148, v148, v7
	v_mul_f32_e32 v149, v149, v7
	v_mul_f32_e32 v150, v150, v7
	v_mul_f32_e32 v151, v151, v7
	v_mul_f32_e32 v148, v40, v148
	v_mul_f32_e32 v149, v41, v149
	v_mul_f32_e32 v150, v42, v150
	v_mul_f32_e32 v151, v43, v151
	v_fma_f32 v148, v28, v148, v56
	v_fma_f32 v149, v29, v149, v57
	v_fma_f32 v150, v30, v150, v58
	v_fma_f32 v151, v31, v151, v59
	v_cvt_pk_bf16_f32 v148, v148, v149
	v_cvt_pk_bf16_f32 v149, v150, v151
	global_store_dwordx2 v[12:13], v[148:149], off offset:-512
	v_mul_f32_e32 v152, v152, v7
	v_mul_f32_e32 v153, v153, v7
	v_mul_f32_e32 v154, v154, v7
	v_mul_f32_e32 v155, v155, v7
	v_mul_f32_e32 v152, v44, v152
	v_mul_f32_e32 v153, v45, v153
	v_mul_f32_e32 v154, v46, v154
	v_mul_f32_e32 v155, v47, v155
	v_fma_f32 v152, v32, v152, v60
	v_fma_f32 v153, v33, v153, v61
	v_fma_f32 v154, v34, v154, v62
	v_fma_f32 v155, v35, v155, v63
	v_cvt_pk_bf16_f32 v152, v152, v153
	v_cvt_pk_bf16_f32 v153, v154, v155
	global_store_dwordx2 v[12:13], v[152:153], off
	v_mul_f32_e32 v230, v230, v7
	v_mul_f32_e32 v231, v231, v7
	v_mul_f32_e32 v232, v232, v7
	v_mul_f32_e32 v233, v233, v7
	v_mul_f32_e32 v230, v48, v230
	v_mul_f32_e32 v231, v49, v231
	v_mul_f32_e32 v232, v50, v232
	v_mul_f32_e32 v233, v51, v233
	v_fma_f32 v230, v36, v230, v64
	v_fma_f32 v231, v37, v231, v65
	v_fma_f32 v232, v38, v232, v66
	v_fma_f32 v233, v39, v233, v67
	v_cvt_pk_bf16_f32 v230, v230, v231
	v_cvt_pk_bf16_f32 v231, v232, v233
	global_store_dwordx2 v[12:13], v[230:231], off offset:512
	v_lshl_add_u64 v[12:13], v[12:13], 0, s[40:41]
	s_branch .LBB0_434
